# NA: rel-pos-bias LDS reads hoisted above QK MFMAs, exec-masked serialized loads -> v_cndmask
# speedup vs baseline: 1.0059x; 1.0059x over previous
; template <int ND> ...
;     ...
;     __builtin_amdgcn_s_setprio(1);
; #pragma unroll
;     for (int kk = 0; kk < 2; ++kk)
; #pragma unroll
;         for (int u = 0; u < 2 * ND; ++u) {
;             const bf16x8 kf = *(const LAS bf16x8*)(lds + kbase + (key0[u >> 1] + (u & 1) * 16 + fr) * 144 + kk * 64 + fq * 16);
;             sc[u] = mfma16(kf, qf[kk], sc[u]); }
;     __builtin_amdgcn_s_setprio(0);
;     if (loc) {
; #pragma unroll
;         for (int g = 0; g < ND; ++g)
; #pragma unroll
;             for (int i = 0; i < 4; ++i) {
;                 const int ck0 = cst + fq * 4 + i, ck1 = ck0 + 16;
;                 const int rel0 = min(max(ck0 - cq + 15, 0), 30), rel1 = min(max(ck1 - cq + 15, 0), 30);
;                 const bool v0 = (ck0 >= c0w) && (ck0 < c0w + 16), v1 = (ck1 >= c0w) && (ck1 < c0w + 16);
;                 sc[2 * g][i] = v0 ? sc[2 * g][i] + rpb[dr[g] * 31 + rel0] : -INFINITY;
;                 sc[2 * g + 1][i] = v1 ? sc[2 * g + 1][i] + rpb[dr[g] * 31 + rel1] : -INFINITY; }
;     }
;     float mx = -INFINITY;
; #pragma unroll
;     for (int u = 0; u < 2 * ND; ++u) mx = fmaxf(mx, fmaxf(fmaxf(sc[u][0], sc[u][1]), fmaxf(sc[u][2], sc[u][3])));
;     mx = xmax16(mx); mx = xmax32(mx);
;     const float m_new = fmaxf(m_run, mx);
;     const float m_use = (m_new == -INFINITY) ? 0.f : m_new;
;     const float alpha = __builtin_amdgcn_exp2f(m_run - m_use);
;     float ps_sum = 0.f; bf16x8 pf[ND];
; #pragma unroll
;     for (int g = 0; g < ND; ++g) { float pv[8];
; #pragma unroll
;         for (int i = 0; i < 4; ++i) { pv[i] = __builtin_amdgcn_exp2f(sc[2 * g][i] - m_use); pv[4 + i] = __builtin_amdgcn_exp2f(sc[2 * g + 1][i] - m_use); ps_sum += pv[i] + pv[4 + i]; }
;         u32x4 pw; pw.x = pk_bf16(pv[0], pv[1]); pw.y = pk_bf16(pv[2], pv[3]); pw.z = pk_bf16(pv[4], pv[5]); pw.w = pk_bf16(pv[6], pv[7]);
;         pf[g] = as_bf8(pw); }
;     l_run = l_run * alpha + ps_sum; m_run = m_new;
;     __builtin_amdgcn_s_setprio(1);
; #pragma unroll
;     for (int d = 0; d < 4; ++d) { O[d] = O[d] * alpha;
; #pragma unroll
;         for (int g = 0; g < ND; ++g) {
;             const u32x2 va = *(const LAS u32x2*)(lds + vbase + (d * 16 + fr) * vstr + (key0[g] + fq * 4) * 2);
;             const u32x2 vb = *(const LAS u32x2*)(lds + vbase + (d * 16 + fr) * vstr + (key0[g] + 16 + fq * 4) * 2);
;             u32x4 vw; vw.x = va.x; vw.y = va.y; vw.z = vb.x; vw.w = vb.y;
.LBB0_775:
	v_add_u32_e32 v219, 0x1e764, v192
	v_add_u32_e32 v220, 0x1e764, v193
	v_add_u32_e32 v221, 0x1e764, v194
	v_add_u32_e32 v222, 0x1e764, v195
	v_add_u32_e32 v223, 0x1e764, v206
	v_add_u32_e32 v224, 0x1e764, v207
	v_add_u32_e32 v225, 0x1e764, v208
	v_add_u32_e32 v226, 0x1e764, v209
	ds_read_b32 v227, v219
	ds_read_b32 v219, v219 offset:124
	ds_read_b32 v234, v220
	ds_read_b32 v220, v220 offset:124
	ds_read_b32 v235, v221
	ds_read_b32 v221, v221 offset:124
	ds_read_b32 v248, v222
	ds_read_b32 v222, v222 offset:124
	ds_read_b32 v249, v223
	ds_read_b32 v223, v223 offset:124
	ds_read_b32 v250, v224
	ds_read_b32 v224, v224 offset:124
	s_setprio 1
	v_add_u32_e32 v2, v166, v191
	ds_read_b128 v[92:95], v2 offset:6912
	v_add_u32_e32 v0, v175, v210
	ds_read_b128 v[84:87], v0
	ds_read_b128 v[88:91], v2
	s_waitcnt lgkmcnt(2)
	ds_read_b32 v251, v225
	ds_read_b32 v225, v225 offset:124
	ds_read_b32 v3, v226
	ds_read_b32 v226, v226 offset:124
	v_mfma_f32_16x16x32_bf16 v[198:201], v[92:95], v[4:7], 0
	ds_read_b128 v[92:95], v2 offset:9216
	s_waitcnt lgkmcnt(0)
	v_mfma_f32_16x16x32_bf16 v[212:215], v[92:95], v[4:7], 0
	ds_read_b128 v[92:95], v0 offset:64
	v_mfma_f32_16x16x32_bf16 v[84:87], v[84:87], v[4:7], 0
	s_waitcnt lgkmcnt(0)
	v_mfma_f32_16x16x32_bf16 v[96:99], v[92:95], v[8:11], v[84:87]
	s_nop 5
	ds_read_b128 v[84:87], v2 offset:64
	v_mfma_f32_16x16x32_bf16 v[88:91], v[88:91], v[4:7], 0
	s_waitcnt lgkmcnt(0)
	v_mfma_f32_16x16x32_bf16 v[92:95], v[84:87], v[8:11], v[88:91]
	ds_read_b128 v[84:87], v2 offset:6976
	s_nop 4
	ds_read_b128 v[88:91], v2 offset:9280
	s_waitcnt lgkmcnt(1)
	v_mfma_f32_16x16x32_bf16 v[84:87], v[84:87], v[8:11], v[198:201]
	s_waitcnt lgkmcnt(0)
	v_mfma_f32_16x16x32_bf16 v[88:91], v[88:91], v[8:11], v[212:215]
	s_setprio 0
	v_mov_b32_e32 v216, 0xff800000
	s_waitcnt lgkmcnt(0)
	v_add_f32_e32 v227, v96, v227
	v_cndmask_b32_e64 v2, v216, v227, s[64:65]
	v_add_f32_e32 v234, v92, v234
	v_cndmask_b32_e64 v0, v216, v234, s[90:91]
	v_add_f32_e32 v235, v97, v235
	v_cndmask_b32_e64 v96, v216, v235, s[74:75]
	v_add_f32_e32 v248, v93, v248
	v_cndmask_b32_e64 v92, v216, v248, s[96:97]
	v_add_f32_e32 v249, v98, v249
	v_cndmask_b32_e64 v97, v216, v249, s[8:9]
	v_add_f32_e32 v250, v94, v250
	v_cndmask_b32_e64 v93, v216, v250, s[86:87]
	v_add_f32_e32 v251, v99, v251
	v_cndmask_b32_e64 v98, v216, v251, s[60:61]
	v_add_f32_e32 v3, v95, v3
	v_cndmask_b32_e64 v94, v216, v3, s[52:53]
	v_add_f32_e32 v219, v84, v219
	v_cndmask_b32_e64 v99, v216, v219, s[64:65]
	v_add_f32_e32 v220, v88, v220
	v_cndmask_b32_e64 v95, v216, v220, s[90:91]
	v_add_f32_e32 v221, v85, v221
	v_cndmask_b32_e64 v88, v216, v221, s[74:75]
	v_add_f32_e32 v222, v89, v222
	v_cndmask_b32_e64 v84, v216, v222, s[96:97]
	v_add_f32_e32 v223, v86, v223
	v_cndmask_b32_e64 v212, v216, v223, s[8:9]
	v_add_f32_e32 v224, v90, v224
	v_cndmask_b32_e64 v85, v216, v224, s[86:87]
	v_add_f32_e32 v225, v87, v225
	v_cndmask_b32_e64 v90, v216, v225, s[60:61]
	v_add_f32_e32 v226, v91, v226
	v_cndmask_b32_e64 v86, v216, v226, s[52:53]
	v_max_f32_e32 v3, v98, v98
	v_max_f32_e32 v87, v97, v97
	v_max_f32_e32 v3, v87, v3
	v_max_f32_e32 v87, v94, v94
	v_max_f32_e32 v89, v93, v93
	v_max_f32_e32 v87, v89, v87
	v_max3_f32 v3, v2, v96, v3
	v_max3_f32 v87, v0, v92, v87
	v_max3_f32 v3, v3, s71, v87
	v_max_f32_e32 v87, v90, v90
	v_max_f32_e32 v89, v212, v212
	v_max_f32_e32 v87, v89, v87
	v_max_f32_e32 v89, v86, v86
	v_max_f32_e32 v91, v85, v85
	v_max_f32_e32 v89, v91, v89
	v_max3_f32 v87, v99, v88, v87
	v_max3_f32 v89, v95, v84, v89
	v_max3_f32 v3, v3, v87, v89
	v_mov_b32_e32 v87, v3
	s_nop 1
	v_permlane16_swap_b32_e32 v3, v87
	v_max_f32_e32 v87, v87, v87
	v_max_f32_e32 v3, v3, v3
	v_max_f32_e32 v3, v3, v87
	v_mov_b32_e32 v87, v3
	s_nop 1
	v_permlane32_swap_b32_e32 v3, v87
	v_max3_f32 v3, v188, v3, v87
	v_cmp_neq_f32_e32 vcc, s71, v3
	s_nop 1
	v_cndmask_b32_e32 v87, 0, v3, vcc
	v_sub_f32_e32 v2, v2, v87
	v_sub_f32_e32 v0, v0, v87
	v_exp_f32_e32 v2, v2
	v_exp_f32_e32 v91, v0
	v_sub_f32_e32 v0, v96, v87
	v_sub_f32_e32 v89, v92, v87
	v_exp_f32_e32 v0, v0
	v_exp_f32_e32 v198, v89
	v_add_f32_e32 v199, v91, v2
	v_sub_f32_e32 v92, v93, v87
	v_sub_f32_e32 v89, v97, v87
	v_pk_add_f32 v[200:201], v[198:199], v[0:1]
	v_exp_f32_e32 v199, v92
	v_pk_add_f32 v[200:201], v[200:201], v[200:201] op_sel_hi:[0,1]
	v_sub_f32_e32 v92, v98, v87
	v_exp_f32_e32 v89, v89
	v_exp_f32_e32 v200, v92
	v_sub_f32_e32 v92, v94, v87
	v_exp_f32_e32 v92, v92
	v_add_f32_e32 v93, v199, v89
	v_sub_f32_e32 v94, v95, v87
	v_exp_f32_e32 v204, v94
	v_pk_add_f32 v[96:97], v[92:93], v[200:201]
	v_sub_f32_e32 v93, v99, v87
	v_pk_add_f32 v[96:97], v[96:97], v[96:97] op_sel_hi:[0,1]
	v_exp_f32_e32 v93, v93
	v_sub_f32_e32 v88, v88, v87
	v_sub_f32_e32 v84, v84, v87
	v_exp_f32_e32 v96, v88
	v_exp_f32_e32 v94, v84
	v_cvt_pk_bf16_f32 v88, v2, v0
	v_add_f32_e32 v95, v204, v93
	v_sub_f32_e32 v0, v212, v87
	v_pk_add_f32 v[98:99], v[94:95], v[96:97]
	v_exp_f32_e32 v95, v0
	v_sub_f32_e32 v0, v85, v87
	v_pk_add_f32 v[98:99], v[98:99], v[98:99] op_sel_hi:[0,1]
	v_exp_f32_e32 v97, v0
	v_sub_f32_e32 v0, v90, v87
	v_exp_f32_e32 v98, v0
	v_sub_f32_e32 v0, v86, v87
	v_cvt_pk_bf16_f32 v89, v89, v200
	v_exp_f32_e32 v200, v0
	v_sub_f32_e32 v188, v188, v87
	v_exp_f32_e32 v0, v188
	v_add_f32_e32 v201, v97, v95
	v_pk_add_f32 v[84:85], v[200:201], v[98:99]
	v_cvt_pk_bf16_f32 v90, v91, v198
	v_cvt_pk_bf16_f32 v91, v199, v92
	s_nop 0
	v_add_f32_e32 v2, v84, v85
	v_fmac_f32_e32 v2, v189, v0
	v_cvt_pk_bf16_f32 v84, v93, v96
	v_cvt_pk_bf16_f32 v85, v95, v98
	v_cvt_pk_bf16_f32 v86, v204, v94
	v_cvt_pk_bf16_f32 v87, v97, v200
	s_setprio 1
	v_add_u32_e32 v99, 0, v190
	v_add_u32_e32 v98, 0, v211
	v_add_u32_e32 v94, 0xb000, v99
	ds_read_b64 v[92:93], v98 offset:46080
	ds_read2_b64 v[94:97], v94 offset0:132 offset1:144
	v_pk_mul_f32 v[70:71], v[70:71], v[0:1] op_sel_hi:[1,0]
	v_pk_mul_f32 v[68:69], v[68:69], v[0:1] op_sel_hi:[1,0]
	v_pk_mul_f32 v[82:83], v[82:83], v[0:1] op_sel_hi:[1,0]
	v_pk_mul_f32 v[80:81], v[80:81], v[0:1] op_sel_hi:[1,0]
	v_pk_mul_f32 v[74:75], v[74:75], v[0:1] op_sel_hi:[1,0]
	v_pk_mul_f32 v[72:73], v[72:73], v[0:1] op_sel_hi:[1,0]
	s_waitcnt lgkmcnt(0)
; #define LAS __attribute__((address_space(3)))
; __device__ __forceinline__ f32x4 mfma16(bf16x8 a, bf16x8 b, f32x4 c) { return __builtin_amdgcn_mfma_f32_16x16x32_bf16(a, b, c, 0, 0, 0); }
; template <int ND> ...
;     ...
;     for (int d = 0; d < 4; ++d) { O[d] = O[d] * alpha;
; #pragma unroll
;         for (int g = 0; g < ND; ++g) {
;             const u32x2 va = *(const LAS u32x2*)(lds + vbase + (d * 16 + fr) * vstr + (key0[g] + fq * 4) * 2);
;             const u32x2 vb = *(const LAS u32x2*)(lds + vbase + (d * 16 + fr) * vstr + (key0[g] + 16 + fq * 4) * 2);
;             u32x4 vw; vw.x = va.x; vw.y = va.y; vw.z = vb.x; vw.w = vb.y;
;             O[d] = mfma16(as_bf8(vw), pf[g], O[d]); } }
; __device__ __forceinline__ void na_item(int wv, const Params& p, int l, int it, LAS unsigned char* lds) {
;     ...
;             for (; rel + 1 < hi; rel += 2) { const int key0[2] = {(rel - p0) * 64 + cst, (rel + 1 - p0) * 64 + cst}; const int dr[2] = {(r0 + rel - off) - r + 7, (r0 + rel + 1 - off) - r + 7};
;                 na_step<2>(lds, NB_KLOC, NB_VLOC, 656, key0, true, dr, rpb, qf, fr, fq, lane, cst, cq, c0w, m_run, l_run, O); }
	v_mfma_f32_16x16x32_bf16 v[68:71], v[92:95], v[88:91], v[68:71]
	ds_read_b64 v[94:95], v99 offset:46240
	v_mov_b32_e32 v92, v96
	v_mov_b32_e32 v93, v97
	v_pk_mul_f32 v[78:79], v[78:79], v[0:1] op_sel_hi:[1,0]
	v_pk_mul_f32 v[76:77], v[76:77], v[0:1] op_sel_hi:[1,0]
	v_add_u32_e32 v0, 0x12f00, v98
	s_waitcnt lgkmcnt(0)
	v_mfma_f32_16x16x32_bf16 v[68:71], v[92:95], v[84:87], v[68:71]
	v_add_u32_e32 v94, 0xd800, v99
	ds_read_b64 v[92:93], v98 offset:56576
	ds_read2_b64 v[94:97], v94 offset0:164 offset1:176
	s_waitcnt lgkmcnt(0)
	v_mfma_f32_16x16x32_bf16 v[80:83], v[92:95], v[88:91], v[80:83]
	ds_read_b64 v[94:95], v99 offset:56736
	v_mov_b32_e32 v92, v96
	v_mov_b32_e32 v93, v97
	s_waitcnt lgkmcnt(0)
	s_nop 0
	v_mfma_f32_16x16x32_bf16 v[80:83], v[92:95], v[84:87], v[80:83]
	v_add_u32_e32 v92, 0x10600, v98
	v_add_u32_e32 v94, 0x10620, v99
	ds_read_b64 v[92:93], v92
	ds_read_b64 v[94:95], v94
	s_waitcnt lgkmcnt(0)
	v_mfma_f32_16x16x32_bf16 v[72:75], v[92:95], v[88:91], v[72:75]
	v_add_u32_e32 v92, 0x10680, v99
	v_add_u32_e32 v94, 0x106a0, v99
	ds_read_b64 v[92:93], v92
	ds_read_b64 v[94:95], v94
	s_waitcnt lgkmcnt(0)
	v_mfma_f32_16x16x32_bf16 v[72:75], v[92:95], v[84:87], v[72:75]
	ds_read_b64 v[92:93], v0
	v_add_u32_e32 v0, 0x12f20, v99
	ds_read_b64 v[94:95], v0
	v_add_u32_e32 v0, 0x12f80, v99
	s_waitcnt lgkmcnt(0)
	v_mfma_f32_16x16x32_bf16 v[76:79], v[92:95], v[88:91], v[76:79]
	ds_read_b64 v[88:89], v0
	v_add_u32_e32 v0, 0x12fa0, v99
	ds_read_b64 v[90:91], v0
	s_waitcnt lgkmcnt(0)
	v_mfma_f32_16x16x32_bf16 v[76:79], v[88:91], v[84:87], v[76:79]
	s_setprio 0
	s_add_i32 s47, s47, 2
	v_add_u32_e32 v190, 0x100, v190
	v_add_u32_e32 v191, 0x4800, v191
	v_add_u32_e32 v192, 0xf8, v192
	v_add_u32_e32 v193, 0xf8, v193
	v_add_u32_e32 v194, 0xf8, v194
	v_add_u32_e32 v195, 0xf8, v195
	v_add_u32_e32 v206, 0xf8, v206
	v_add_u32_e32 v207, 0xf8, v207
	v_add_u32_e32 v208, 0xf8, v208
	v_add_u32_e32 v209, 0xf8, v209
	v_add_u32_e32 v210, 0x4800, v210
	s_cmp_lt_i32 s47, s46
	v_add_u32_e32 v211, 0x100, v211
	s_cbranch_scc0 .LBB0_810
	v_mov_b32_e32 v188, v3
	v_mov_b32_e32 v189, v2
	s_branch .LBB0_775

; template <int ND> ...
;     ...
;     __builtin_amdgcn_s_setprio(1);
; #pragma unroll
;     for (int kk = 0; kk < 2; ++kk)
; #pragma unroll
;         for (int u = 0; u < 2 * ND; ++u) {
;             const bf16x8 kf = *(const LAS bf16x8*)(lds + kbase + (key0[u >> 1] + (u & 1) * 16 + fr) * 144 + kk * 64 + fq * 16);
;             sc[u] = mfma16(kf, qf[kk], sc[u]); }
;     __builtin_amdgcn_s_setprio(0);
;     if (loc) {
; #pragma unroll
;         for (int g = 0; g < ND; ++g)
; #pragma unroll
;             for (int i = 0; i < 4; ++i) {
;                 const int ck0 = cst + fq * 4 + i, ck1 = ck0 + 16;
;                 const int rel0 = min(max(ck0 - cq + 15, 0), 30), rel1 = min(max(ck1 - cq + 15, 0), 30);
;                 const bool v0 = (ck0 >= c0w) && (ck0 < c0w + 16), v1 = (ck1 >= c0w) && (ck1 < c0w + 16);
;                 sc[2 * g][i] = v0 ? sc[2 * g][i] + rpb[dr[g] * 31 + rel0] : -INFINITY;
;                 sc[2 * g + 1][i] = v1 ? sc[2 * g + 1][i] + rpb[dr[g] * 31 + rel1] : -INFINITY; }
;     }
;     float mx = -INFINITY;
; #pragma unroll
;     for (int u = 0; u < 2 * ND; ++u) mx = fmaxf(mx, fmaxf(fmaxf(sc[u][0], sc[u][1]), fmaxf(sc[u][2], sc[u][3])));
;     mx = xmax16(mx); mx = xmax32(mx);
;     const float m_new = fmaxf(m_run, mx);
;     const float m_use = (m_new == -INFINITY) ? 0.f : m_new;
;     const float alpha = __builtin_amdgcn_exp2f(m_run - m_use);
;     float ps_sum = 0.f; bf16x8 pf[ND];
; #pragma unroll
;     for (int g = 0; g < ND; ++g) { float pv[8];
; #pragma unroll
;         for (int i = 0; i < 4; ++i) { pv[i] = __builtin_amdgcn_exp2f(sc[2 * g][i] - m_use); pv[4 + i] = __builtin_amdgcn_exp2f(sc[2 * g + 1][i] - m_use); ps_sum += pv[i] + pv[4 + i]; }
;         u32x4 pw; pw.x = pk_bf16(pv[0], pv[1]); pw.y = pk_bf16(pv[2], pv[3]); pw.z = pk_bf16(pv[4], pv[5]); pw.w = pk_bf16(pv[6], pv[7]);
;         pf[g] = as_bf8(pw); }
;     l_run = l_run * alpha + ps_sum; m_run = m_new;
;     __builtin_amdgcn_s_setprio(1);
; #pragma unroll
;     for (int d = 0; d < 4; ++d) { O[d] = O[d] * alpha;
; #pragma unroll
;         for (int g = 0; g < ND; ++g) {
;             const u32x2 va = *(const LAS u32x2*)(lds + vbase + (d * 16 + fr) * vstr + (key0[g] + fq * 4) * 2);
;             const u32x2 vb = *(const LAS u32x2*)(lds + vbase + (d * 16 + fr) * vstr + (key0[g] + 16 + fq * 4) * 2);
;             u32x4 vw; vw.x = va.x; vw.y = va.y; vw.z = vb.x; vw.w = vb.y;
.LBB0_811:
	s_sub_i32 s3, s4, s3
	s_lshl_b32 s3, s3, 6
	s_or_b32 s3, s3, s56
	s_add_i32 s46, s82, s4
	s_mulk_i32 s46, 0x7c
	s_add_i32 s46, s46, 0
	s_add_i32 s46, s46, 0x1e400
	v_lshl_add_u32 v219, v147, 2, s46
	v_lshl_add_u32 v220, v146, 2, s46
	v_lshl_add_u32 v221, v149, 2, s46
	v_lshl_add_u32 v222, v148, 2, s46
	v_lshl_add_u32 v223, v151, 2, s46
	v_lshl_add_u32 v224, v150, 2, s46
	v_lshl_add_u32 v225, v153, 2, s46
	v_lshl_add_u32 v226, v152, 2, s46
	ds_read_b32 v219, v219 offset:868
	ds_read_b32 v220, v220 offset:868
	ds_read_b32 v221, v221 offset:868
	ds_read_b32 v222, v222 offset:868
	ds_read_b32 v223, v223 offset:868
	ds_read_b32 v224, v224 offset:868
	ds_read_b32 v225, v225 offset:868
	ds_read_b32 v226, v226 offset:868
	s_setprio 1
	v_add_u32_e32 v0, s3, v107
	v_mad_u64_u32 v[96:97], s[4:5], v0, s55, v[108:109]
	ds_read_b128 v[84:87], v96
	ds_read_b128 v[92:95], v96 offset:64
	ds_read_b128 v[88:91], v96 offset:2304
	s_waitcnt lgkmcnt(2)
	v_mfma_f32_16x16x32_bf16 v[84:87], v[84:87], v[4:7], 0
	s_waitcnt lgkmcnt(1)
	v_mfma_f32_16x16x32_bf16 v[84:87], v[92:95], v[8:11], v[84:87]
	ds_read_b128 v[92:95], v96 offset:2368
	s_waitcnt lgkmcnt(1)
	v_mfma_f32_16x16x32_bf16 v[88:91], v[88:91], v[4:7], 0
	s_waitcnt lgkmcnt(0)
	v_mfma_f32_16x16x32_bf16 v[88:91], v[92:95], v[8:11], v[88:91]
	s_setprio 0
	v_mov_b32_e32 v227, 0xff800000
	s_waitcnt lgkmcnt(0)
	s_nop 4
	v_add_f32_e32 v219, v84, v219
	v_cndmask_b32_e64 v92, v227, v219, s[64:65]
	v_add_f32_e32 v220, v88, v220
	v_cndmask_b32_e64 v0, v227, v220, s[90:91]
	v_add_f32_e32 v221, v85, v221
	v_cndmask_b32_e64 v88, v227, v221, s[74:75]
	v_add_f32_e32 v222, v89, v222
	v_cndmask_b32_e64 v84, v227, v222, s[96:97]
	v_add_f32_e32 v223, v86, v223
	v_cndmask_b32_e64 v89, v227, v223, s[8:9]
	v_add_f32_e32 v224, v90, v224
	v_cndmask_b32_e64 v85, v227, v224, s[86:87]
	v_add_f32_e32 v225, v87, v225
	v_cndmask_b32_e64 v90, v227, v225, s[60:61]
	v_add_f32_e32 v226, v91, v226
	v_cndmask_b32_e64 v86, v227, v226, s[52:53]
	v_max_f32_e32 v87, v90, v90
	v_max_f32_e32 v91, v89, v89
	v_max_f32_e32 v87, v91, v87
	v_max_f32_e32 v91, v86, v86
	v_max_f32_e32 v93, v85, v85
	v_max_f32_e32 v91, v93, v91
	v_max3_f32 v87, v92, v88, v87
	v_max3_f32 v91, v0, v84, v91
	v_max3_f32 v87, v87, s71, v91
	v_mov_b32_e32 v91, v87
	s_nop 1
	v_permlane16_swap_b32_e32 v87, v91
	v_max_f32_e32 v91, v91, v91
	v_max_f32_e32 v87, v87, v87
	v_max_f32_e32 v87, v87, v91
	v_mov_b32_e32 v91, v87
	s_nop 1
	v_permlane32_swap_b32_e32 v87, v91
	v_max3_f32 v97, v3, v87, v91
	v_cmp_neq_f32_e32 vcc, s71, v97
	s_nop 1
	v_cndmask_b32_e32 v87, 0, v97, vcc
	v_sub_f32_e32 v91, v92, v87
	v_sub_f32_e32 v0, v0, v87
	v_exp_f32_e32 v91, v91
	v_exp_f32_e32 v98, v0
	v_sub_f32_e32 v0, v88, v87
	v_sub_f32_e32 v84, v84, v87
	v_exp_f32_e32 v0, v0
	v_exp_f32_e32 v92, v84
	v_add_f32_e32 v93, v98, v91
	v_sub_f32_e32 v84, v89, v87
	v_sub_f32_e32 v3, v3, v87
	v_pk_add_f32 v[94:95], v[92:93], v[0:1]
	v_exp_f32_e32 v93, v84
	v_sub_f32_e32 v84, v85, v87
	v_pk_add_f32 v[94:95], v[94:95], v[94:95] op_sel_hi:[0,1]
	v_exp_f32_e32 v99, v84
	v_sub_f32_e32 v84, v90, v87
	v_exp_f32_e32 v94, v84
	v_sub_f32_e32 v84, v86, v87
	v_exp_f32_e32 v88, v84
	v_exp_f32_e32 v96, v3
	v_add_f32_e32 v89, v99, v93
	v_pk_add_f32 v[84:85], v[88:89], v[94:95]
	s_nop 0
	v_add_f32_e32 v95, v84, v85
	v_cvt_pk_bf16_f32 v84, v91, v0
	v_cvt_pk_bf16_f32 v85, v93, v94
	v_cvt_pk_bf16_f32 v86, v98, v92
	v_cvt_pk_bf16_f32 v87, v99, v88
	v_fmac_f32_e32 v95, v2, v96
	s_setprio 1
	v_add_lshl_u32 v0, s3, v106, 1
	v_add_lshl_u32 v2, s3, v154, 1
	v_add_u32_e32 v3, v156, v0
	v_add_u32_e32 v92, v156, v2
	ds_read_b64 v[88:89], v3 offset:46080
	ds_read_b64 v[90:91], v92 offset:46080
	v_pk_mul_f32 v[70:71], v[70:71], v[96:97] op_sel_hi:[1,0]
	v_pk_mul_f32 v[68:69], v[68:69], v[96:97] op_sel_hi:[1,0]
	v_pk_mul_f32 v[82:83], v[82:83], v[96:97] op_sel_hi:[1,0]
	v_pk_mul_f32 v[80:81], v[80:81], v[96:97] op_sel_hi:[1,0]
	s_waitcnt lgkmcnt(0)
	v_mfma_f32_16x16x32_bf16 v[68:71], v[88:91], v[84:87], v[68:71]
	ds_read_b64 v[88:89], v3 offset:56576
	ds_read_b64 v[90:91], v92 offset:56576
	v_add_u32_e32 v0, v157, v0
	v_add_u32_e32 v2, v157, v2
	s_waitcnt lgkmcnt(0)
	v_mfma_f32_16x16x32_bf16 v[80:83], v[88:91], v[84:87], v[80:83]
	ds_read_b64 v[88:89], v0 offset:20992
	ds_read_b64 v[90:91], v2 offset:20992
	v_pk_mul_f32 v[74:75], v[74:75], v[96:97] op_sel_hi:[1,0]
	v_pk_mul_f32 v[72:73], v[72:73], v[96:97] op_sel_hi:[1,0]
	v_pk_mul_f32 v[78:79], v[78:79], v[96:97] op_sel_hi:[1,0]
	v_pk_mul_f32 v[76:77], v[76:77], v[96:97] op_sel_hi:[1,0]
	s_waitcnt lgkmcnt(0)
	v_mfma_f32_16x16x32_bf16 v[72:75], v[88:91], v[84:87], v[72:75]
	ds_read_b64 v[88:89], v0 offset:31488
	ds_read_b64 v[90:91], v2 offset:31488
	s_waitcnt lgkmcnt(0)
	v_mfma_f32_16x16x32_bf16 v[76:79], v[88:91], v[84:87], v[76:79]
	s_setprio 0
	v_mov_b32_e32 v3, v97
	v_mov_b32_e32 v2, v95
	s_branch .LBB0_737
